# rg_scan2 backward step loop: next step's RA1 row loaded one step ahead into a spare quad
# baseline (speedup 1.0000x reference)
; __device__ __forceinline__ float rg_sp(float lam) { const float z = __expf(-lam); const float sp = z < 0.25f ? z * (1.0f - z * (0.5f - z * (0.33333334f - z * (0.25f - z * (0.2f - z * (0.16666667f - z * 0.14285715f)))))) : __logf(1.0f + z); return -8.0f * 1.4426950408889634f * sp; }
; __device__ __forceinline__ void rg_unpack8(const u32x4 w, float* v) { v[0] = bflo(w.x); v[1] = bfhi(w.x); v[2] = bflo(w.y); v[3] = bfhi(w.y); v[4] = bflo(w.z); v[5] = bfhi(w.z); v[6] = bflo(w.w); v[7] = bfhi(w.w); }
; __device__ __forceinline__ void rg_consts8(const float* bap, const float* bxp, const float* lamp, int idx, float* ba, float* bx, float* sp) {
; #pragma unroll
;     for (int h = 0; h < 2; ++h) { const f32x4 a = *(const f32x4*)(bap + idx + 4 * h), x = *(const f32x4*)(bxp + idx + 4 * h), l = *(const f32x4*)(lamp + idx + 4 * h);
; #pragma unroll
;         for (int e = 0; e < 4; ++e) { ba[4 * h + e] = a[e]; bx[4 * h + e] = x[e]; sp[4 * h + e] = rg_sp(l[e]); } }
; __device__ __forceinline__ void rg_scan2_phase(const bf16_t* RA0, bf16_t* RI0, const bf16_t* RA1, const bf16_t* RI1, const bf16_t* XCV, const float* bap, const float* bxp, const float* lamp, const float* CAR, bf16_t* Gb, int gtid, int ngt) {
;     ...
;         rg_fold8(CAR, b, 1, 2 * cbk, cg, h); rg_consts8(bap, bxp, lamp, 1280 + 8 * cg, ba, bx, sp);
;         asm volatile("s_waitcnt vmcnt(0)" ::: "memory");
; #pragma unroll 4
;         for (int i = 63; i >= 0; --i) { const size_t off = (size_t)(row0 + i) * DRNN + 8 * cg;
.LBB0_1413:
	s_andn2_saveexec_b64 s[6:7], s[24:25]
	v_fmamk_f32 v19, v20, 0xbe124925, v201
	v_fma_f32 v19, -v20, v19, s47
	v_fma_f32 v19, -v20, v19, s45
	v_fma_f32 v19, -v20, v19, s48
	v_fma_f32 v19, -v20, v19, 0.5
	v_fma_f32 v19, -v20, v19, 1.0
	v_mul_f32_e32 v19, v20, v19
	s_or_b64 exec, exec, s[6:7]
	s_waitcnt vmcnt(0)
	v_mul_f32_e32 v73, 0xc138aa3b, v18
	v_mul_f32_e32 v74, 0xc138aa3b, v17
	v_mul_f32_e32 v75, 0xc138aa3b, v16
	v_mul_f32_e32 v76, 0xc138aa3b, v25
	v_mul_f32_e32 v77, 0xc138aa3b, v24
	v_mul_f32_e32 v78, 0xc138aa3b, v23
	v_mul_f32_e32 v79, 0xc138aa3b, v22
	v_mul_f32_e32 v80, 0xc138aa3b, v19
	v_lshl_add_u64 v[38:39], s[10:11], 0, v[32:33]
	v_lshl_add_u64 v[40:41], s[8:9], 0, v[32:33]
	s_movk_i32 s1, 0xffc0
	s_mov_b64 s[100:101], 0x19827000
	v_lshl_add_u64 v[172:173], v[38:39], 0, v[36:37]
	v_lshl_add_u64 v[172:173], v[172:173], 0, s[100:101]
	global_load_dwordx4 v[168:171], v[172:173], off offset:1536
	s_waitcnt vmcnt(0)
	s_branch .LBB0_1417

; __device__ __forceinline__ unsigned pk2(float lo, float hi) { f32x2_pk v = {lo, hi}; bf16x2_pk b = __builtin_convertvector(v, bf16x2_pk); return __builtin_bit_cast(unsigned, b); }
; __device__ __forceinline__ float sigmoidf_(float x) { return __builtin_amdgcn_rcpf(1.0f + __expf(-x)); }
; __device__ __forceinline__ void rg_unpack8(const u32x4 w, float* v) { v[0] = bflo(w.x); v[1] = bfhi(w.x); v[2] = bflo(w.y); v[3] = bfhi(w.y); v[4] = bflo(w.z); v[5] = bfhi(w.z); v[6] = bflo(w.w); v[7] = bfhi(w.w); }
; __device__ __forceinline__ void rg_ab(float ra, float ri, float x, float ba, float bx, float sp, float& a, float& b) {
;     const float r = sigmoidf_(ra + ba), ig = sigmoidf_(ri + bx); const float l2 = r * sp; a = exp2f(l2);
;     const float x2 = 1.3862943611198906f * l2;
;     const float om = x2 > -0.125f ? -x2 * (1.0f + x2 * (0.5f + x2 * (0.16666667f + x2 * (0.041666668f + x2 * 0.0083333338f)))) : 1.0f - __expf(x2);
;     b = __builtin_amdgcn_sqrtf(om) * (ig * x);
; }
; __device__ __forceinline__ void rg_scan2_phase(const bf16_t* RA0, bf16_t* RI0, const bf16_t* RA1, const bf16_t* RI1, const bf16_t* XCV, const float* bap, const float* bxp, const float* lamp, const float* CAR, bf16_t* Gb, int gtid, int ngt) {
;     ...
;         for (int i = 63; i >= 0; --i) { const size_t off = (size_t)(row0 + i) * DRNN + 8 * cg;
;             float ra[8], ri[8], xv[8], hf[8], gv[8]; rg_unpack8(*(const u32x4*)(RA1 + off), ra); rg_unpack8(*(const u32x4*)(RI1 + off), ri); rg_unpack8(*(const u32x4*)(XCV + off), xv);
;             rg_unpack8(*(const u32x4*)(RI0 + off), hf); rg_unpack8(*(const u32x4*)(Gb + off), gv);
; #pragma unroll
;             for (int e = 0; e < 8; ++e) { float a, bb; rg_ab(ra[e], ri[e], xv[e], ba[e], bx[e], sp[e], a, bb); h[e] = a * h[e] + bb; gv[e] *= hf[e] + h[e]; }
;             u32x4 o; o.x = pk2(gv[0], gv[1]); o.y = pk2(gv[2], gv[3]); o.z = pk2(gv[4], gv[5]); o.w = pk2(gv[6], gv[7]); *(u32x4*)(Gb + off) = o; }
.LBB0_1417:
	v_lshl_add_u64 v[42:43], v[38:39], 0, v[36:37]
	v_add_co_u32_e32 v16, vcc, 0x19827000, v42
	v_lshl_add_u64 v[44:45], v[40:41], 0, v[36:37]
	s_nop 0
	v_addc_co_u32_e32 v17, vcc, 0, v43, vcc
	s_nop 1
	v_mov_b32_e32 v32, v168
	v_mov_b32_e32 v33, v169
	v_mov_b32_e32 v34, v170
	v_mov_b32_e32 v35, v171
	global_load_dwordx4 v[168:171], v[16:17], off offset:-1024
	v_add_co_u32_e32 v16, vcc, 0x27000, v44
	s_nop 0
	v_lshlrev_b32_e32 v47, 16, v32
	v_addc_co_u32_e32 v17, vcc, 0, v45, vcc
	v_add_co_u32_e32 v20, vcc, 0x8a27000, v42
	global_load_dwordx4 v[16:19], v[16:17], off offset:1536
	s_nop 0
	v_addc_co_u32_e32 v21, vcc, 0, v43, vcc
	v_add_co_u32_e32 v22, vcc, 0x13e27000, v42
	v_add_f32_e32 v47, v0, v47
	s_nop 0
	v_addc_co_u32_e32 v23, vcc, 0, v43, vcc
	v_add_co_u32_e32 v28, vcc, 0x3027000, v42
	global_load_dwordx4 v[24:27], v[20:21], off offset:1536
	s_nop 0
	global_load_dwordx4 v[20:23], v[22:23], off offset:1536
	v_addc_co_u32_e32 v29, vcc, 0, v43, vcc
	global_load_dwordx4 v[28:31], v[28:29], off offset:1536
	v_mul_f32_e32 v47, 0xbfb8aa3b, v47
	v_exp_f32_e32 v47, v47
	s_nop 0
	v_add_f32_e32 v47, 1.0, v47
	v_rcp_f32_e32 v47, v47
	s_nop 0
	v_mul_f32_e32 v47, v79, v47
	v_mul_f32_e32 v49, 0x3fb17218, v47
	v_mul_f32_e32 v92, 0x3fb8aa3b, v49
	v_exp_f32_e32 v92, v92
	v_fmamk_f32 v93, v49, 0x3c088889, v202
	v_fmaak_f32 v93, v49, v93, 0x3e2aaaab
	v_fma_f32 v93, v49, v93, 0.5
	v_fma_f32 v93, v49, v93, 1.0
	v_mul_f32_e64 v93, v93, -v49
	v_sub_f32_e32 v92, 1.0, v92
	v_cmp_nlt_f32_e32 vcc, s5, v49
	s_nop 1
	v_cndmask_b32_e32 v51, v93, v92, vcc
	v_and_b32_e32 v32, 0xffff0000, v32
	v_add_f32_e32 v32, v1, v32
	v_mul_f32_e32 v32, 0xbfb8aa3b, v32
	v_exp_f32_e32 v32, v32
	s_nop 0
	v_add_f32_e32 v32, 1.0, v32
	v_rcp_f32_e32 v32, v32
	s_nop 0
	v_mul_f32_e32 v53, v78, v32
	v_mul_f32_e32 v49, 0x3fb17218, v53
	v_mul_f32_e32 v92, 0x3fb8aa3b, v49
	v_exp_f32_e32 v92, v92
	v_fmamk_f32 v93, v49, 0x3c088889, v202
	v_fmaak_f32 v93, v49, v93, 0x3e2aaaab
	v_fma_f32 v93, v49, v93, 0.5
	v_fma_f32 v93, v49, v93, 1.0
	v_mul_f32_e64 v93, v93, -v49
	v_sub_f32_e32 v92, 1.0, v92
	v_cmp_nlt_f32_e32 vcc, s5, v49
	s_nop 1
	v_cndmask_b32_e32 v32, v93, v92, vcc
	v_lshlrev_b32_e32 v49, 16, v33
	v_add_f32_e32 v49, v2, v49
	v_mul_f32_e32 v49, 0xbfb8aa3b, v49
	v_exp_f32_e32 v49, v49
	s_nop 0
	v_add_f32_e32 v49, 1.0, v49
	v_rcp_f32_e32 v49, v49
	s_nop 0
	v_mul_f32_e32 v57, v77, v49
	v_mul_f32_e32 v55, 0x3fb17218, v57
	v_mul_f32_e32 v92, 0x3fb8aa3b, v55
	v_exp_f32_e32 v92, v92
	v_fmamk_f32 v93, v55, 0x3c088889, v202
	v_fmaak_f32 v93, v55, v93, 0x3e2aaaab
	v_fma_f32 v93, v55, v93, 0.5
	v_fma_f32 v93, v55, v93, 1.0
	v_mul_f32_e64 v93, v93, -v55
	v_sub_f32_e32 v92, 1.0, v92
	v_cmp_nlt_f32_e32 vcc, s5, v55
	s_nop 1
	v_cndmask_b32_e32 v49, v93, v92, vcc
	v_and_b32_e32 v33, 0xffff0000, v33
	v_add_f32_e32 v33, v3, v33
	v_mul_f32_e32 v33, 0xbfb8aa3b, v33
	v_exp_f32_e32 v33, v33
	s_nop 0
	v_add_f32_e32 v33, 1.0, v33
	v_rcp_f32_e32 v33, v33
	s_nop 0
	v_mul_f32_e32 v66, v76, v33
	v_mul_f32_e32 v55, 0x3fb17218, v66
	v_mul_f32_e32 v92, 0x3fb8aa3b, v55
	v_exp_f32_e32 v92, v92
	v_fmamk_f32 v93, v55, 0x3c088889, v202
	v_fmaak_f32 v93, v55, v93, 0x3e2aaaab
	v_fma_f32 v93, v55, v93, 0.5
	v_fma_f32 v93, v55, v93, 1.0
	v_mul_f32_e64 v93, v93, -v55
	v_sub_f32_e32 v92, 1.0, v92
	v_cmp_nlt_f32_e32 vcc, s5, v55
	s_nop 1
	v_cndmask_b32_e32 v33, v93, v92, vcc
	v_lshlrev_b32_e32 v55, 16, v34
	v_add_f32_e32 v55, v8, v55
	v_mul_f32_e32 v55, 0xbfb8aa3b, v55
	v_exp_f32_e32 v55, v55
	s_nop 0
	v_add_f32_e32 v55, 1.0, v55
	v_rcp_f32_e32 v55, v55
	s_nop 0
	v_mul_f32_e32 v61, v75, v55
	v_mul_f32_e32 v59, 0x3fb17218, v61
	v_mul_f32_e32 v92, 0x3fb8aa3b, v59
	v_exp_f32_e32 v92, v92
	v_fmamk_f32 v93, v59, 0x3c088889, v202
	v_fmaak_f32 v93, v59, v93, 0x3e2aaaab
	v_fma_f32 v93, v59, v93, 0.5
	v_fma_f32 v93, v59, v93, 1.0
	v_mul_f32_e64 v93, v93, -v59
	v_sub_f32_e32 v92, 1.0, v92
	v_cmp_nlt_f32_e32 vcc, s5, v59
	s_nop 1
	v_cndmask_b32_e32 v55, v93, v92, vcc
	v_and_b32_e32 v34, 0xffff0000, v34
	v_add_f32_e32 v34, v9, v34
	v_mul_f32_e32 v34, 0xbfb8aa3b, v34
	v_exp_f32_e32 v34, v34
	s_nop 0
	v_add_f32_e32 v34, 1.0, v34
	v_rcp_f32_e32 v34, v34
	s_nop 0
	v_mul_f32_e32 v68, v74, v34
	v_mul_f32_e32 v34, 0x3fb17218, v68
	v_mul_f32_e32 v92, 0x3fb8aa3b, v34
	v_exp_f32_e32 v92, v92
	v_fmamk_f32 v93, v34, 0x3c088889, v202
	v_fmaak_f32 v93, v34, v93, 0x3e2aaaab
	v_fma_f32 v93, v34, v93, 0.5
	v_fma_f32 v93, v34, v93, 1.0
	v_mul_f32_e64 v93, v93, -v34
	v_sub_f32_e32 v92, 1.0, v92
	v_cmp_nlt_f32_e32 vcc, s5, v34
	s_nop 1
	v_cndmask_b32_e32 v67, v93, v92, vcc
	v_lshlrev_b32_e32 v34, 16, v35
	v_add_f32_e32 v34, v10, v34
	v_mul_f32_e32 v34, 0xbfb8aa3b, v34
	v_exp_f32_e32 v34, v34
	s_nop 0
	v_add_f32_e32 v34, 1.0, v34
	v_rcp_f32_e32 v34, v34
	s_nop 0
	v_mul_f32_e32 v62, v73, v34
	v_mul_f32_e32 v34, 0x3fb17218, v62
	v_mul_f32_e32 v92, 0x3fb8aa3b, v34
	v_exp_f32_e32 v92, v92
	v_fmamk_f32 v93, v34, 0x3c088889, v202
	v_fmaak_f32 v93, v34, v93, 0x3e2aaaab
	v_fma_f32 v93, v34, v93, 0.5
	v_fma_f32 v93, v34, v93, 1.0
	v_mul_f32_e64 v93, v93, -v34
	v_sub_f32_e32 v92, 1.0, v92
	v_cmp_nlt_f32_e32 vcc, s5, v34
	s_nop 1
	v_cndmask_b32_e32 v59, v93, v92, vcc
	v_and_b32_e32 v34, 0xffff0000, v35
	v_add_f32_e32 v34, v11, v34
	v_mul_f32_e32 v34, 0xbfb8aa3b, v34
	v_exp_f32_e32 v34, v34
	s_nop 0
	v_add_f32_e32 v34, 1.0, v34
	v_rcp_f32_e32 v34, v34
	s_nop 0
	v_mul_f32_e32 v35, v80, v34
	v_mul_f32_e32 v63, 0x3fb17218, v35
	v_mul_f32_e32 v92, 0x3fb8aa3b, v63
	v_exp_f32_e32 v92, v92
	v_fmamk_f32 v93, v63, 0x3c088889, v202
	v_fmaak_f32 v93, v63, v93, 0x3e2aaaab
	v_fma_f32 v93, v63, v93, 0.5
	v_fma_f32 v93, v63, v93, 1.0
	v_mul_f32_e64 v93, v93, -v63
	v_sub_f32_e32 v92, 1.0, v92
	v_cmp_nlt_f32_e32 vcc, s5, v63
	s_nop 1
	v_cndmask_b32_e32 v34, v93, v92, vcc
	v_cmp_gt_f32_e32 vcc, s82, v62
	s_waitcnt vmcnt(2)
; __device__ __forceinline__ unsigned pk2(float lo, float hi) { f32x2_pk v = {lo, hi}; bf16x2_pk b = __builtin_convertvector(v, bf16x2_pk); return __builtin_bit_cast(unsigned, b); }
; __device__ __forceinline__ float sigmoidf_(float x) { return __builtin_amdgcn_rcpf(1.0f + __expf(-x)); }
; __device__ __forceinline__ void rg_unpack8(const u32x4 w, float* v) { v[0] = bflo(w.x); v[1] = bfhi(w.x); v[2] = bflo(w.y); v[3] = bfhi(w.y); v[4] = bflo(w.z); v[5] = bfhi(w.z); v[6] = bflo(w.w); v[7] = bfhi(w.w); }
; __device__ __forceinline__ void rg_ab(float ra, float ri, float x, float ba, float bx, float sp, float& a, float& b) {
;     const float r = sigmoidf_(ra + ba), ig = sigmoidf_(ri + bx); const float l2 = r * sp; a = exp2f(l2);
;     const float x2 = 1.3862943611198906f * l2;
;     const float om = x2 > -0.125f ? -x2 * (1.0f + x2 * (0.5f + x2 * (0.16666667f + x2 * (0.041666668f + x2 * 0.0083333338f)))) : 1.0f - __expf(x2);
;     b = __builtin_amdgcn_sqrtf(om) * (ig * x);
; }
; __device__ __forceinline__ void rg_scan2_phase(const bf16_t* RA0, bf16_t* RI0, const bf16_t* RA1, const bf16_t* RI1, const bf16_t* XCV, const float* bap, const float* bxp, const float* lamp, const float* CAR, bf16_t* Gb, int gtid, int ngt) {
;     ...
;         for (int i = 63; i >= 0; --i) { const size_t off = (size_t)(row0 + i) * DRNN + 8 * cg;
;             float ra[8], ri[8], xv[8], hf[8], gv[8]; rg_unpack8(*(const u32x4*)(RA1 + off), ra); rg_unpack8(*(const u32x4*)(RI1 + off), ri); rg_unpack8(*(const u32x4*)(XCV + off), xv);
;             rg_unpack8(*(const u32x4*)(RI0 + off), hf); rg_unpack8(*(const u32x4*)(Gb + off), gv);
; #pragma unroll
;             for (int e = 0; e < 8; ++e) { float a, bb; rg_ab(ra[e], ri[e], xv[e], ba[e], bx[e], sp[e], a, bb); h[e] = a * h[e] + bb; gv[e] *= hf[e] + h[e]; }
;             u32x4 o; o.x = pk2(gv[0], gv[1]); o.y = pk2(gv[2], gv[3]); o.z = pk2(gv[4], gv[5]); o.w = pk2(gv[6], gv[7]); *(u32x4*)(Gb + off) = o; }
	v_lshlrev_b32_e32 v65, 16, v27
	s_waitcnt vmcnt(1)
	v_lshlrev_b32_e32 v69, 16, v23
	v_cndmask_b32_e32 v64, 0, v221, vcc
	v_add_f32_e32 v62, v62, v64
	v_lshlrev_b32_e32 v64, 16, v19
	v_add_f32_e32 v64, v14, v64
	v_mul_f32_e32 v64, 0xbfb8aa3b, v64
	v_exp_f32_e32 v62, v62
	v_exp_f32_e32 v64, v64
	v_cndmask_b32_e32 v63, 0, v220, vcc
	s_waitcnt vmcnt(0)
	v_lshlrev_b32_e32 v81, 16, v31
	v_ldexp_f32 v62, v62, v63
	v_add_f32_e32 v63, 1.0, v64
	v_rcp_f32_e32 v64, v63
	v_sqrt_f32_e32 v63, v59
	v_cmp_gt_f32_e32 vcc, s82, v35
	s_mov_b64 s[2:3], 0x3027600
	v_mul_f32_e32 v59, v64, v65
	v_mul_f32_e32 v64, v59, v63
	v_pk_fma_f32 v[64:65], v[58:59], v[62:63], v[64:65] op_sel_hi:[1,1,0]
	v_cndmask_b32_e32 v59, 0, v221, vcc
	v_add_f32_e32 v58, v64, v69
	v_mul_f32_e32 v65, v58, v81
	v_cndmask_b32_e32 v58, 0, v220, vcc
	v_cmp_gt_f32_e32 vcc, s82, v61
	v_add_f32_e32 v35, v35, v59
	v_exp_f32_e32 v35, v35
	v_cndmask_b32_e32 v62, 0, v221, vcc
	v_add_f32_e32 v61, v61, v62
	v_lshlrev_b32_e32 v62, 16, v18
	v_add_f32_e32 v62, v12, v62
	v_mul_f32_e32 v62, 0xbfb8aa3b, v62
	v_exp_f32_e32 v61, v61
	v_exp_f32_e32 v62, v62
	v_cndmask_b32_e32 v59, 0, v220, vcc
	v_ldexp_f32 v82, v35, v58
	v_ldexp_f32 v58, v61, v59
	v_add_f32_e32 v59, 1.0, v62
	v_rcp_f32_e32 v61, v59
	v_sqrt_f32_e32 v59, v55
	v_lshlrev_b32_e32 v35, 16, v26
	v_and_b32_e32 v18, 0xffff0000, v18
	v_mul_f32_e32 v55, v61, v35
	v_add_f32_e32 v18, v13, v18
	v_mul_f32_e32 v62, v55, v59
	v_cmp_gt_f32_e32 vcc, s82, v68
	v_mul_f32_e32 v18, 0xbfb8aa3b, v18
	v_pk_fma_f32 v[62:63], v[54:55], v[58:59], v[62:63] op_sel_hi:[1,1,0]
	v_cndmask_b32_e32 v55, 0, v221, vcc
	v_exp_f32_e32 v18, v18
	v_add_f32_e32 v55, v68, v55
	v_exp_f32_e32 v55, v55
	v_cndmask_b32_e32 v54, 0, v220, vcc
	v_add_f32_e32 v18, 1.0, v18
	v_rcp_f32_e32 v18, v18
	v_ldexp_f32 v54, v55, v54
	v_sqrt_f32_e32 v55, v67
	v_and_b32_e32 v26, 0xffff0000, v26
	v_mul_f32_e32 v61, v18, v26
	v_cmp_gt_f32_e32 vcc, s82, v57
	v_mul_f32_e32 v18, v61, v55
	v_pk_fma_f32 v[60:61], v[60:61], v[54:55], v[18:19] op_sel_hi:[1,1,0]
	v_lshlrev_b32_e32 v54, 16, v17
	v_cndmask_b32_e32 v26, 0, v221, vcc
	v_add_f32_e32 v54, v6, v54
	v_add_f32_e32 v26, v57, v26
	v_mul_f32_e32 v54, 0xbfb8aa3b, v54
	v_exp_f32_e32 v26, v26
	v_exp_f32_e32 v55, v54
	v_lshlrev_b32_e32 v69, 16, v22
	v_and_b32_e32 v22, 0xffff0000, v22
	v_add_f32_e32 v18, v60, v22
	v_cndmask_b32_e32 v22, 0, v220, vcc
	v_ldexp_f32 v54, v26, v22
	v_add_f32_e32 v22, 1.0, v55
	v_rcp_f32_e32 v22, v22
	v_and_b32_e32 v17, 0xffff0000, v17
	v_sqrt_f32_e32 v55, v49
	v_add_f32_e32 v17, v7, v17
	v_lshlrev_b32_e32 v81, 16, v30
	v_and_b32_e32 v30, 0xffff0000, v30
	v_mul_f32_e32 v17, 0xbfb8aa3b, v17
	v_mul_f32_e32 v30, v18, v30
	v_lshlrev_b32_e32 v18, 16, v25
	v_exp_f32_e32 v17, v17
	v_mul_f32_e32 v49, v22, v18
	v_mul_f32_e32 v18, v49, v55
	v_lshlrev_b32_e32 v26, 16, v21
	v_pk_fma_f32 v[58:59], v[48:49], v[54:55], v[18:19] op_sel_hi:[1,1,0]
	v_cmp_gt_f32_e32 vcc, s82, v66
	v_add_f32_e32 v18, v58, v26
	v_add_f32_e32 v17, 1.0, v17
	v_cndmask_b32_e32 v26, 0, v221, vcc
	v_add_f32_e32 v26, v66, v26
	v_rcp_f32_e32 v17, v17
	v_exp_f32_e32 v26, v26
	v_sqrt_f32_e32 v49, v33
	v_lshlrev_b32_e32 v57, 16, v29
	v_mul_f32_e32 v59, v18, v57
	v_and_b32_e32 v18, 0xffff0000, v25
	v_cndmask_b32_e32 v22, 0, v220, vcc
	v_mul_f32_e32 v57, v17, v18
	v_ldexp_f32 v48, v26, v22
	v_mul_f32_e32 v18, v57, v49
	v_and_b32_e32 v21, 0xffff0000, v21
	v_pk_fma_f32 v[56:57], v[56:57], v[48:49], v[18:19] op_sel_hi:[1,1,0]
	v_and_b32_e32 v22, 0xffff0000, v29
	v_add_f32_e32 v17, v56, v21
	v_mul_f32_e32 v21, v17, v22
	v_lshlrev_b32_e32 v17, 16, v16
	v_add_f32_e32 v17, v4, v17
	v_mul_f32_e32 v17, 0xbfb8aa3b, v17
	v_exp_f32_e32 v17, v17
	v_cmp_gt_f32_e32 vcc, s82, v47
	v_sqrt_f32_e32 v49, v51
	v_lshlrev_b32_e32 v18, 16, v24
	v_cndmask_b32_e32 v26, 0, v221, vcc
	v_add_f32_e32 v17, 1.0, v17
	v_add_f32_e32 v26, v47, v26
	v_rcp_f32_e32 v17, v17
	v_exp_f32_e32 v26, v26
	v_cndmask_b32_e32 v25, 0, v220, vcc
	v_and_b32_e32 v16, 0xffff0000, v16
	v_mul_f32_e32 v47, v17, v18
	v_ldexp_f32 v48, v26, v25
	v_mul_f32_e32 v18, v47, v49
	v_lshlrev_b32_e32 v22, 16, v20
	v_pk_fma_f32 v[54:55], v[46:47], v[48:49], v[18:19] op_sel_hi:[1,1,0]
	v_cmp_gt_f32_e32 vcc, s82, v53
	v_add_f32_e32 v16, v5, v16
	v_add_f32_e32 v17, v54, v22
	v_cndmask_b32_e32 v22, 0, v221, vcc
	v_mul_f32_e32 v16, 0xbfb8aa3b, v16
	v_add_f32_e32 v22, v53, v22
	v_exp_f32_e32 v25, v16
	v_exp_f32_e32 v22, v22
	v_lshlrev_b32_e32 v29, 16, v28
	v_cndmask_b32_e32 v18, 0, v220, vcc
	v_mul_f32_e32 v26, v17, v29
	v_add_f32_e32 v17, 1.0, v25
	v_ldexp_f32 v16, v22, v18
	v_rcp_f32_e32 v22, v17
	v_sqrt_f32_e32 v17, v32
	v_and_b32_e32 v18, 0xffff0000, v24
	v_lshl_add_u64 v[70:71], v[42:43], 0, s[2:3]
	v_mul_f32_e32 v53, v22, v18
	v_mul_f32_e32 v18, v53, v17
	v_pk_fma_f32 v[52:53], v[52:53], v[16:17], v[18:19] op_sel_hi:[1,1,0]
	v_and_b32_e32 v16, 0xffff0000, v19
	v_add_f32_e32 v16, v15, v16
	v_mul_f32_e32 v16, 0xbfb8aa3b, v16
	v_exp_f32_e32 v16, v16
	s_mov_b32 s2, 0x19826000
	v_add_f32_e32 v35, v62, v69
	v_add_co_u32_e32 v48, vcc, s2, v42
	v_add_f32_e32 v16, 1.0, v16
	v_rcp_f32_e32 v16, v16
	v_mul_f32_e32 v35, v35, v81
	v_and_b32_e32 v18, 0xffff0000, v27
	v_addc_co_u32_e32 v49, vcc, 0, v43, vcc
	v_sqrt_f32_e32 v83, v34
	v_mul_f32_e32 v51, v16, v18
	v_cvt_pk_bf16_f32 v18, v35, v30
	s_nop 1
	v_mov_b32_e32 v32, v168
	v_mov_b32_e32 v33, v169
	v_mov_b32_e32 v34, v170
	v_mov_b32_e32 v35, v171
	global_load_dwordx4 v[168:171], v[48:49], off offset:512
	s_mov_b32 s2, 0x26000
	v_and_b32_e32 v20, 0xffff0000, v20
	v_add_co_u32_e32 v46, vcc, s2, v44
	v_and_b32_e32 v24, 0xffff0000, v28
	v_add_f32_e32 v17, v52, v20
	v_addc_co_u32_e32 v47, vcc, 0, v45, vcc
; __device__ __forceinline__ unsigned pk2(float lo, float hi) { f32x2_pk v = {lo, hi}; bf16x2_pk b = __builtin_convertvector(v, bf16x2_pk); return __builtin_bit_cast(unsigned, b); }
; __device__ __forceinline__ float sigmoidf_(float x) { return __builtin_amdgcn_rcpf(1.0f + __expf(-x)); }
; __device__ __forceinline__ void rg_unpack8(const u32x4 w, float* v) { v[0] = bflo(w.x); v[1] = bfhi(w.x); v[2] = bflo(w.y); v[3] = bfhi(w.y); v[4] = bflo(w.z); v[5] = bfhi(w.z); v[6] = bflo(w.w); v[7] = bfhi(w.w); }
; __device__ __forceinline__ void rg_ab(float ra, float ri, float x, float ba, float bx, float sp, float& a, float& b) {
;     const float r = sigmoidf_(ra + ba), ig = sigmoidf_(ri + bx); const float l2 = r * sp; a = exp2f(l2);
;     const float x2 = 1.3862943611198906f * l2;
;     const float om = x2 > -0.125f ? -x2 * (1.0f + x2 * (0.5f + x2 * (0.16666667f + x2 * (0.041666668f + x2 * 0.0083333338f)))) : 1.0f - __expf(x2);
;     b = __builtin_amdgcn_sqrtf(om) * (ig * x);
; }
; __device__ __forceinline__ void rg_scan2_phase(const bf16_t* RA0, bf16_t* RI0, const bf16_t* RA1, const bf16_t* RI1, const bf16_t* XCV, const float* bap, const float* bxp, const float* lamp, const float* CAR, bf16_t* Gb, int gtid, int ngt) {
;     ...
;         for (int i = 63; i >= 0; --i) { const size_t off = (size_t)(row0 + i) * DRNN + 8 * cg;
;             float ra[8], ri[8], xv[8], hf[8], gv[8]; rg_unpack8(*(const u32x4*)(RA1 + off), ra); rg_unpack8(*(const u32x4*)(RI1 + off), ri); rg_unpack8(*(const u32x4*)(XCV + off), xv);
;             rg_unpack8(*(const u32x4*)(RI0 + off), hf); rg_unpack8(*(const u32x4*)(Gb + off), gv);
; #pragma unroll
;             for (int e = 0; e < 8; ++e) { float a, bb; rg_ab(ra[e], ri[e], xv[e], ba[e], bx[e], sp[e], a, bb); h[e] = a * h[e] + bb; gv[e] *= hf[e] + h[e]; }
;             u32x4 o; o.x = pk2(gv[0], gv[1]); o.y = pk2(gv[2], gv[3]); o.z = pk2(gv[4], gv[5]); o.w = pk2(gv[6], gv[7]); *(u32x4*)(Gb + off) = o; }
	s_mov_b32 s2, 0x8a26000
	v_mul_f32_e32 v17, v17, v24
	v_mul_f32_e32 v16, v51, v83
	v_add_co_u32_e32 v66, vcc, s2, v42
	v_and_b32_e32 v19, 0xffff0000, v23
	v_pk_fma_f32 v[50:51], v[50:51], v[82:83], v[16:17] op_sel_hi:[1,1,0]
	v_addc_co_u32_e32 v67, vcc, 0, v43, vcc
	s_mov_b32 s2, 0x13e26000
	v_and_b32_e32 v20, 0xffff0000, v31
	v_add_f32_e32 v16, v50, v19
	v_add_co_u32_e32 v68, vcc, s2, v42
	v_mul_f32_e32 v19, v16, v20
	s_nop 0
	v_addc_co_u32_e32 v69, vcc, 0, v43, vcc
	v_cvt_pk_bf16_f32 v16, v26, v17
	v_cvt_pk_bf16_f32 v17, v59, v21
	v_cvt_pk_bf16_f32 v19, v65, v19
	v_add_co_u32_e32 v28, vcc, 0x3026000, v42
	global_store_dwordx4 v[70:71], v[16:19], off
	s_nop 0
	v_addc_co_u32_e32 v29, vcc, 0, v43, vcc
	global_load_dwordx4 v[16:19], v[46:47], off offset:3072
	global_load_dwordx4 v[24:27], v[66:67], off offset:3072
	global_load_dwordx4 v[20:23], v[68:69], off offset:3072
	s_nop 0
	v_lshlrev_b32_e32 v51, 16, v32
	global_load_dwordx4 v[28:31], v[28:29], off offset:3072
	v_add_f32_e32 v51, v0, v51
	v_mul_f32_e32 v51, 0xbfb8aa3b, v51
	v_exp_f32_e32 v51, v51
	s_nop 0
	v_add_f32_e32 v51, 1.0, v51
	v_rcp_f32_e32 v51, v51
	s_nop 0
	v_mul_f32_e32 v51, v79, v51
	v_mul_f32_e32 v55, 0x3fb17218, v51
	v_mul_f32_e32 v92, 0x3fb8aa3b, v55
	v_exp_f32_e32 v92, v92
	v_fmamk_f32 v93, v55, 0x3c088889, v202
	v_fmaak_f32 v93, v55, v93, 0x3e2aaaab
	v_fma_f32 v93, v55, v93, 0.5
	v_fma_f32 v93, v55, v93, 1.0
	v_mul_f32_e64 v93, v93, -v55
	v_sub_f32_e32 v92, 1.0, v92
	v_cmp_nlt_f32_e32 vcc, s5, v55
	s_nop 1
	v_cndmask_b32_e32 v53, v93, v92, vcc
	v_and_b32_e32 v32, 0xffff0000, v32
	v_add_f32_e32 v32, v1, v32
	v_mul_f32_e32 v32, 0xbfb8aa3b, v32
	v_exp_f32_e32 v32, v32
	s_nop 0
	v_add_f32_e32 v32, 1.0, v32
	v_rcp_f32_e32 v32, v32
	s_nop 0
	v_mul_f32_e32 v81, v78, v32
	v_mul_f32_e32 v55, 0x3fb17218, v81
	v_mul_f32_e32 v92, 0x3fb8aa3b, v55
	v_exp_f32_e32 v92, v92
	v_fmamk_f32 v93, v55, 0x3c088889, v202
	v_fmaak_f32 v93, v55, v93, 0x3e2aaaab
	v_fma_f32 v93, v55, v93, 0.5
	v_fma_f32 v93, v55, v93, 1.0
	v_mul_f32_e64 v93, v93, -v55
	v_sub_f32_e32 v92, 1.0, v92
	v_cmp_nlt_f32_e32 vcc, s5, v55
	s_nop 1
	v_cndmask_b32_e32 v32, v93, v92, vcc
	v_lshlrev_b32_e32 v55, 16, v33
	v_add_f32_e32 v55, v2, v55
	v_mul_f32_e32 v55, 0xbfb8aa3b, v55
	v_exp_f32_e32 v55, v55
	s_nop 0
	v_add_f32_e32 v55, 1.0, v55
	v_rcp_f32_e32 v55, v55
	s_nop 0
	v_mul_f32_e32 v57, v77, v55
	v_mul_f32_e32 v59, 0x3fb17218, v57
	v_mul_f32_e32 v92, 0x3fb8aa3b, v59
	v_exp_f32_e32 v92, v92
	v_fmamk_f32 v93, v59, 0x3c088889, v202
	v_fmaak_f32 v93, v59, v93, 0x3e2aaaab
	v_fma_f32 v93, v59, v93, 0.5
	v_fma_f32 v93, v59, v93, 1.0
	v_mul_f32_e64 v93, v93, -v59
	v_sub_f32_e32 v92, 1.0, v92
	v_cmp_nlt_f32_e32 vcc, s5, v59
	s_nop 1
	v_cndmask_b32_e32 v55, v93, v92, vcc
	v_and_b32_e32 v33, 0xffff0000, v33
	v_add_f32_e32 v33, v3, v33
	v_mul_f32_e32 v33, 0xbfb8aa3b, v33
	v_exp_f32_e32 v33, v33
	s_nop 0
	v_add_f32_e32 v33, 1.0, v33
	v_rcp_f32_e32 v33, v33
	s_nop 0
	v_mul_f32_e32 v82, v76, v33
	v_mul_f32_e32 v59, 0x3fb17218, v82
	v_mul_f32_e32 v92, 0x3fb8aa3b, v59
	v_exp_f32_e32 v92, v92
	v_fmamk_f32 v93, v59, 0x3c088889, v202
	v_fmaak_f32 v93, v59, v93, 0x3e2aaaab
	v_fma_f32 v93, v59, v93, 0.5
	v_fma_f32 v93, v59, v93, 1.0
	v_mul_f32_e64 v93, v93, -v59
	v_sub_f32_e32 v92, 1.0, v92
	v_cmp_nlt_f32_e32 vcc, s5, v59
	s_nop 1
	v_cndmask_b32_e32 v33, v93, v92, vcc
	v_lshlrev_b32_e32 v59, 16, v34
	v_add_f32_e32 v59, v8, v59
	v_mul_f32_e32 v59, 0xbfb8aa3b, v59
	v_exp_f32_e32 v59, v59
	s_nop 0
	v_add_f32_e32 v59, 1.0, v59
	v_rcp_f32_e32 v59, v59
	s_nop 0
	v_mul_f32_e32 v61, v75, v59
	v_mul_f32_e32 v63, 0x3fb17218, v61
	v_mul_f32_e32 v92, 0x3fb8aa3b, v63
	v_exp_f32_e32 v92, v92
	v_fmamk_f32 v93, v63, 0x3c088889, v202
	v_fmaak_f32 v93, v63, v93, 0x3e2aaaab
	v_fma_f32 v93, v63, v93, 0.5
	v_fma_f32 v93, v63, v93, 1.0
	v_mul_f32_e64 v93, v93, -v63
	v_sub_f32_e32 v92, 1.0, v92
	v_cmp_nlt_f32_e32 vcc, s5, v63
	s_nop 1
	v_cndmask_b32_e32 v59, v93, v92, vcc
	v_and_b32_e32 v34, 0xffff0000, v34
	v_add_f32_e32 v34, v9, v34
	v_mul_f32_e32 v34, 0xbfb8aa3b, v34
	v_exp_f32_e32 v34, v34
	s_nop 0
	v_add_f32_e32 v34, 1.0, v34
	v_rcp_f32_e32 v34, v34
	s_nop 0
	v_mul_f32_e32 v84, v74, v34
	v_mul_f32_e32 v34, 0x3fb17218, v84
	v_mul_f32_e32 v92, 0x3fb8aa3b, v34
	v_exp_f32_e32 v92, v92
	v_fmamk_f32 v93, v34, 0x3c088889, v202
	v_fmaak_f32 v93, v34, v93, 0x3e2aaaab
	v_fma_f32 v93, v34, v93, 0.5
	v_fma_f32 v93, v34, v93, 1.0
	v_mul_f32_e64 v93, v93, -v34
	v_sub_f32_e32 v92, 1.0, v92
	v_cmp_nlt_f32_e32 vcc, s5, v34
	s_nop 1
	v_cndmask_b32_e32 v83, v93, v92, vcc
	v_lshlrev_b32_e32 v34, 16, v35
	v_add_f32_e32 v34, v10, v34
	v_mul_f32_e32 v34, 0xbfb8aa3b, v34
	v_exp_f32_e32 v34, v34
	s_nop 0
	v_add_f32_e32 v34, 1.0, v34
	v_rcp_f32_e32 v34, v34
	s_nop 0
	v_mul_f32_e32 v65, v73, v34
	v_mul_f32_e32 v34, 0x3fb17218, v65
	v_mul_f32_e32 v92, 0x3fb8aa3b, v34
	v_exp_f32_e32 v92, v92
	v_fmamk_f32 v93, v34, 0x3c088889, v202
	v_fmaak_f32 v93, v34, v93, 0x3e2aaaab
	v_fma_f32 v93, v34, v93, 0.5
	v_fma_f32 v93, v34, v93, 1.0
	v_mul_f32_e64 v93, v93, -v34
	v_sub_f32_e32 v92, 1.0, v92
	v_cmp_nlt_f32_e32 vcc, s5, v34
	s_nop 1
	v_cndmask_b32_e32 v63, v93, v92, vcc
	v_and_b32_e32 v34, 0xffff0000, v35
	v_add_f32_e32 v34, v11, v34
	v_mul_f32_e32 v34, 0xbfb8aa3b, v34
	v_exp_f32_e32 v34, v34
	s_nop 0
	v_add_f32_e32 v34, 1.0, v34
	v_rcp_f32_e32 v34, v34
	s_nop 0
	v_mul_f32_e32 v35, v80, v34
	v_mul_f32_e32 v70, 0x3fb17218, v35
	v_mul_f32_e32 v92, 0x3fb8aa3b, v70
	v_exp_f32_e32 v92, v92
	v_fmamk_f32 v93, v70, 0x3c088889, v202
	v_fmaak_f32 v93, v70, v93, 0x3e2aaaab
	v_fma_f32 v93, v70, v93, 0.5
	v_fma_f32 v93, v70, v93, 1.0
	v_mul_f32_e64 v93, v93, -v70
	v_sub_f32_e32 v92, 1.0, v92
	v_cmp_nlt_f32_e32 vcc, s5, v70
	s_nop 1
	v_cndmask_b32_e32 v34, v93, v92, vcc
	v_cmp_gt_f32_e32 vcc, s82, v65
	s_waitcnt vmcnt(0)
; __device__ __forceinline__ unsigned pk2(float lo, float hi) { f32x2_pk v = {lo, hi}; bf16x2_pk b = __builtin_convertvector(v, bf16x2_pk); return __builtin_bit_cast(unsigned, b); }
; __device__ __forceinline__ float sigmoidf_(float x) { return __builtin_amdgcn_rcpf(1.0f + __expf(-x)); }
; __device__ __forceinline__ void rg_unpack8(const u32x4 w, float* v) { v[0] = bflo(w.x); v[1] = bfhi(w.x); v[2] = bflo(w.y); v[3] = bfhi(w.y); v[4] = bflo(w.z); v[5] = bfhi(w.z); v[6] = bflo(w.w); v[7] = bfhi(w.w); }
; __device__ __forceinline__ void rg_ab(float ra, float ri, float x, float ba, float bx, float sp, float& a, float& b) {
;     const float r = sigmoidf_(ra + ba), ig = sigmoidf_(ri + bx); const float l2 = r * sp; a = exp2f(l2);
;     const float x2 = 1.3862943611198906f * l2;
;     const float om = x2 > -0.125f ? -x2 * (1.0f + x2 * (0.5f + x2 * (0.16666667f + x2 * (0.041666668f + x2 * 0.0083333338f)))) : 1.0f - __expf(x2);
;     b = __builtin_amdgcn_sqrtf(om) * (ig * x);
; }
; __device__ __forceinline__ void rg_scan2_phase(const bf16_t* RA0, bf16_t* RI0, const bf16_t* RA1, const bf16_t* RI1, const bf16_t* XCV, const float* bap, const float* bxp, const float* lamp, const float* CAR, bf16_t* Gb, int gtid, int ngt) {
;     ...
;         for (int i = 63; i >= 0; --i) { const size_t off = (size_t)(row0 + i) * DRNN + 8 * cg;
;             float ra[8], ri[8], xv[8], hf[8], gv[8]; rg_unpack8(*(const u32x4*)(RA1 + off), ra); rg_unpack8(*(const u32x4*)(RI1 + off), ri); rg_unpack8(*(const u32x4*)(XCV + off), xv);
;             rg_unpack8(*(const u32x4*)(RI0 + off), hf); rg_unpack8(*(const u32x4*)(Gb + off), gv);
; #pragma unroll
;             for (int e = 0; e < 8; ++e) { float a, bb; rg_ab(ra[e], ri[e], xv[e], ba[e], bx[e], sp[e], a, bb); h[e] = a * h[e] + bb; gv[e] *= hf[e] + h[e]; }
;             u32x4 o; o.x = pk2(gv[0], gv[1]); o.y = pk2(gv[2], gv[3]); o.z = pk2(gv[4], gv[5]); o.w = pk2(gv[6], gv[7]); *(u32x4*)(Gb + off) = o; }
	v_lshlrev_b32_e32 v89, 16, v31
	s_mov_b64 s[2:3], 0x3026c00
	v_cndmask_b32_e32 v71, 0, v221, vcc
	v_add_f32_e32 v65, v65, v71
	v_lshlrev_b32_e32 v71, 16, v19
	v_add_f32_e32 v71, v14, v71
	v_mul_f32_e32 v71, 0xbfb8aa3b, v71
	v_exp_f32_e32 v71, v71
	v_exp_f32_e32 v65, v65
	v_cndmask_b32_e32 v70, 0, v220, vcc
	v_cmp_gt_f32_e32 vcc, s82, v35
	v_add_f32_e32 v71, 1.0, v71
	v_rcp_f32_e32 v85, v71
	v_sqrt_f32_e32 v71, v63
	v_ldexp_f32 v70, v65, v70
	v_lshlrev_b32_e32 v65, 16, v27
	v_mul_f32_e32 v65, v85, v65
	v_mul_f32_e32 v88, v65, v71
	v_lshlrev_b32_e32 v63, 16, v23
	v_pk_fma_f32 v[70:71], v[64:65], v[70:71], v[88:89] op_sel_hi:[1,1,0]
	v_cndmask_b32_e32 v64, 0, v221, vcc
	v_add_f32_e32 v63, v70, v63
	v_mul_f32_e32 v71, v63, v89
	v_cndmask_b32_e32 v63, 0, v220, vcc
	v_cmp_gt_f32_e32 vcc, s82, v61
	v_add_f32_e32 v35, v35, v64
	v_exp_f32_e32 v35, v35
	v_cndmask_b32_e32 v65, 0, v221, vcc
	v_add_f32_e32 v61, v61, v65
	v_lshlrev_b32_e32 v65, 16, v18
	v_add_f32_e32 v65, v12, v65
	v_mul_f32_e32 v65, 0xbfb8aa3b, v65
	v_exp_f32_e32 v61, v61
	v_exp_f32_e32 v65, v65
	v_cndmask_b32_e32 v64, 0, v220, vcc
	v_and_b32_e32 v18, 0xffff0000, v18
	v_ldexp_f32 v64, v61, v64
	v_add_f32_e32 v61, 1.0, v65
	v_add_f32_e32 v18, v13, v18
	v_rcp_f32_e32 v61, v61
	v_mul_f32_e32 v18, 0xbfb8aa3b, v18
	v_exp_f32_e32 v18, v18
	v_sqrt_f32_e32 v65, v59
	v_ldexp_f32 v88, v35, v63
	v_lshlrev_b32_e32 v35, 16, v26
	v_cmp_gt_f32_e32 vcc, s82, v84
	v_mul_f32_e32 v63, v61, v35
	v_add_f32_e32 v18, 1.0, v18
	v_cndmask_b32_e32 v61, 0, v221, vcc
	v_add_f32_e32 v61, v84, v61
	v_mul_f32_e32 v90, v63, v65
	v_exp_f32_e32 v61, v61
	v_rcp_f32_e32 v18, v18
	v_lshlrev_b32_e32 v59, 16, v22
	v_pk_fma_f32 v[64:65], v[62:63], v[64:65], v[90:91] op_sel_hi:[1,1,0]
	v_lshlrev_b32_e32 v85, 16, v30
	v_add_f32_e32 v35, v64, v59
	v_cndmask_b32_e32 v59, 0, v220, vcc
	v_mul_f32_e32 v65, v35, v85
	v_and_b32_e32 v26, 0xffff0000, v26
	v_sqrt_f32_e32 v63, v83
	v_cmp_gt_f32_e32 vcc, s82, v57
	v_lshlrev_b32_e32 v35, 16, v17
	v_ldexp_f32 v62, v61, v59
	v_mul_f32_e32 v61, v18, v26
	v_cndmask_b32_e32 v26, 0, v221, vcc
	v_add_f32_e32 v35, v6, v35
	v_add_f32_e32 v26, v57, v26
	v_mul_f32_e32 v35, 0xbfb8aa3b, v35
	v_exp_f32_e32 v26, v26
	v_exp_f32_e32 v35, v35
	v_mul_f32_e32 v18, v61, v63
	v_and_b32_e32 v22, 0xffff0000, v22
	v_pk_fma_f32 v[62:63], v[60:61], v[62:63], v[18:19] op_sel_hi:[1,1,0]
	v_and_b32_e32 v17, 0xffff0000, v17
	v_add_f32_e32 v18, v62, v22
	v_cndmask_b32_e32 v22, 0, v220, vcc
	v_ldexp_f32 v60, v26, v22
	v_add_f32_e32 v22, 1.0, v35
	v_rcp_f32_e32 v22, v22
	v_sqrt_f32_e32 v61, v55
	v_add_f32_e32 v17, v7, v17
	v_and_b32_e32 v30, 0xffff0000, v30
	v_mul_f32_e32 v17, 0xbfb8aa3b, v17
	v_mul_f32_e32 v30, v18, v30
	v_lshlrev_b32_e32 v18, 16, v25
	v_exp_f32_e32 v17, v17
	v_mul_f32_e32 v59, v22, v18
	v_mul_f32_e32 v18, v59, v61
	v_lshlrev_b32_e32 v26, 16, v21
	v_pk_fma_f32 v[60:61], v[58:59], v[60:61], v[18:19] op_sel_hi:[1,1,0]
	v_cmp_gt_f32_e32 vcc, s82, v82
	v_add_f32_e32 v18, v60, v26
	v_add_f32_e32 v17, 1.0, v17
	v_cndmask_b32_e32 v26, 0, v221, vcc
	v_add_f32_e32 v26, v82, v26
	v_rcp_f32_e32 v17, v17
	v_exp_f32_e32 v26, v26
	v_sqrt_f32_e32 v59, v33
	v_lshlrev_b32_e32 v35, 16, v29
	v_mul_f32_e32 v61, v18, v35
	v_and_b32_e32 v18, 0xffff0000, v25
	v_cndmask_b32_e32 v22, 0, v220, vcc
	v_mul_f32_e32 v57, v17, v18
	v_ldexp_f32 v58, v26, v22
	v_mul_f32_e32 v18, v57, v59
	v_and_b32_e32 v21, 0xffff0000, v21
	v_pk_fma_f32 v[58:59], v[56:57], v[58:59], v[18:19] op_sel_hi:[1,1,0]
	v_and_b32_e32 v22, 0xffff0000, v29
	v_add_f32_e32 v17, v58, v21
	v_mul_f32_e32 v21, v17, v22
	v_lshlrev_b32_e32 v17, 16, v16
	v_add_f32_e32 v17, v4, v17
	v_mul_f32_e32 v17, 0xbfb8aa3b, v17
	v_exp_f32_e32 v17, v17
	v_cmp_gt_f32_e32 vcc, s82, v51
	v_sqrt_f32_e32 v57, v53
	v_lshlrev_b32_e32 v18, 16, v24
	v_cndmask_b32_e32 v26, 0, v221, vcc
	v_add_f32_e32 v17, 1.0, v17
	v_add_f32_e32 v26, v51, v26
	v_rcp_f32_e32 v17, v17
	v_exp_f32_e32 v26, v26
	v_cndmask_b32_e32 v25, 0, v220, vcc
	v_and_b32_e32 v16, 0xffff0000, v16
	v_mul_f32_e32 v55, v17, v18
	v_ldexp_f32 v56, v26, v25
	v_mul_f32_e32 v18, v55, v57
	v_lshlrev_b32_e32 v22, 16, v20
	v_pk_fma_f32 v[56:57], v[54:55], v[56:57], v[18:19] op_sel_hi:[1,1,0]
	v_cmp_gt_f32_e32 vcc, s82, v81
	v_add_f32_e32 v16, v5, v16
	v_add_f32_e32 v17, v56, v22
	v_cndmask_b32_e32 v22, 0, v221, vcc
	v_mul_f32_e32 v16, 0xbfb8aa3b, v16
	v_add_f32_e32 v22, v81, v22
	v_exp_f32_e32 v25, v16
	v_exp_f32_e32 v22, v22
	v_lshlrev_b32_e32 v29, 16, v28
	v_cndmask_b32_e32 v18, 0, v220, vcc
	v_mul_f32_e32 v26, v17, v29
	v_add_f32_e32 v17, 1.0, v25
	v_ldexp_f32 v16, v22, v18
	v_rcp_f32_e32 v22, v17
	v_sqrt_f32_e32 v17, v32
	v_and_b32_e32 v18, 0xffff0000, v24
	v_sqrt_f32_e32 v89, v34
	v_mul_f32_e32 v53, v22, v18
	v_mul_f32_e32 v18, v53, v17
	v_pk_fma_f32 v[54:55], v[52:53], v[16:17], v[18:19] op_sel_hi:[1,1,0]
	v_and_b32_e32 v16, 0xffff0000, v19
	v_add_f32_e32 v16, v15, v16
	v_mul_f32_e32 v16, 0xbfb8aa3b, v16
	v_exp_f32_e32 v16, v16
	s_nop 1
	v_mov_b32_e32 v32, v168
	v_mov_b32_e32 v33, v169
	v_mov_b32_e32 v34, v170
	v_mov_b32_e32 v35, v171
	global_load_dwordx4 v[168:171], v[48:49], off offset:-2048
	v_and_b32_e32 v20, 0xffff0000, v20
	v_and_b32_e32 v18, 0xffff0000, v27
	v_add_f32_e32 v16, 1.0, v16
	v_rcp_f32_e32 v16, v16
	v_and_b32_e32 v24, 0xffff0000, v28
	v_add_f32_e32 v17, v54, v20
	v_mul_f32_e32 v17, v17, v24
	v_mul_f32_e32 v51, v16, v18
	v_mul_f32_e32 v16, v51, v89
	v_and_b32_e32 v19, 0xffff0000, v23
	v_pk_fma_f32 v[52:53], v[50:51], v[88:89], v[16:17] op_sel_hi:[1,1,0]
	v_and_b32_e32 v20, 0xffff0000, v31
	v_add_f32_e32 v16, v52, v19
	v_mul_f32_e32 v19, v16, v20
	v_lshl_add_u64 v[86:87], v[42:43], 0, s[2:3]
	v_cvt_pk_bf16_f32 v16, v26, v17
; __device__ __forceinline__ unsigned pk2(float lo, float hi) { f32x2_pk v = {lo, hi}; bf16x2_pk b = __builtin_convertvector(v, bf16x2_pk); return __builtin_bit_cast(unsigned, b); }
; __device__ __forceinline__ float sigmoidf_(float x) { return __builtin_amdgcn_rcpf(1.0f + __expf(-x)); }
; __device__ __forceinline__ void rg_unpack8(const u32x4 w, float* v) { v[0] = bflo(w.x); v[1] = bfhi(w.x); v[2] = bflo(w.y); v[3] = bfhi(w.y); v[4] = bflo(w.z); v[5] = bfhi(w.z); v[6] = bflo(w.w); v[7] = bfhi(w.w); }
; __device__ __forceinline__ void rg_ab(float ra, float ri, float x, float ba, float bx, float sp, float& a, float& b) {
;     const float r = sigmoidf_(ra + ba), ig = sigmoidf_(ri + bx); const float l2 = r * sp; a = exp2f(l2);
;     const float x2 = 1.3862943611198906f * l2;
;     const float om = x2 > -0.125f ? -x2 * (1.0f + x2 * (0.5f + x2 * (0.16666667f + x2 * (0.041666668f + x2 * 0.0083333338f)))) : 1.0f - __expf(x2);
;     b = __builtin_amdgcn_sqrtf(om) * (ig * x);
; }
; __device__ __forceinline__ void rg_scan2_phase(const bf16_t* RA0, bf16_t* RI0, const bf16_t* RA1, const bf16_t* RI1, const bf16_t* XCV, const float* bap, const float* bxp, const float* lamp, const float* CAR, bf16_t* Gb, int gtid, int ngt) {
;     ...
;         for (int i = 63; i >= 0; --i) { const size_t off = (size_t)(row0 + i) * DRNN + 8 * cg;
;             float ra[8], ri[8], xv[8], hf[8], gv[8]; rg_unpack8(*(const u32x4*)(RA1 + off), ra); rg_unpack8(*(const u32x4*)(RI1 + off), ri); rg_unpack8(*(const u32x4*)(XCV + off), xv);
;             rg_unpack8(*(const u32x4*)(RI0 + off), hf); rg_unpack8(*(const u32x4*)(Gb + off), gv);
; #pragma unroll
;             for (int e = 0; e < 8; ++e) { float a, bb; rg_ab(ra[e], ri[e], xv[e], ba[e], bx[e], sp[e], a, bb); h[e] = a * h[e] + bb; gv[e] *= hf[e] + h[e]; }
;             u32x4 o; o.x = pk2(gv[0], gv[1]); o.y = pk2(gv[2], gv[3]); o.z = pk2(gv[4], gv[5]); o.w = pk2(gv[6], gv[7]); *(u32x4*)(Gb + off) = o; }
	v_cvt_pk_bf16_f32 v17, v61, v21
	v_cvt_pk_bf16_f32 v18, v65, v30
	v_cvt_pk_bf16_f32 v19, v71, v19
	global_store_dwordx4 v[86:87], v[16:19], off
	v_add_co_u32_e32 v28, vcc, 0x3026000, v42
	global_load_dwordx4 v[24:27], v[46:47], off offset:512
	global_load_dwordx4 v[20:23], v[66:67], off offset:512
	global_load_dwordx4 v[16:19], v[68:69], off offset:512
	v_addc_co_u32_e32 v29, vcc, 0, v43, vcc
	global_load_dwordx4 v[28:31], v[28:29], off offset:512
	s_nop 0
	v_lshlrev_b32_e32 v46, 16, v32
	v_add_f32_e32 v46, v0, v46
	v_mul_f32_e32 v46, 0xbfb8aa3b, v46
	v_exp_f32_e32 v46, v46
	s_nop 0
	v_add_f32_e32 v46, 1.0, v46
	v_rcp_f32_e32 v46, v46
	s_nop 0
	v_mul_f32_e32 v53, v79, v46
	v_mul_f32_e32 v46, 0x3fb17218, v53
	v_mul_f32_e32 v92, 0x3fb8aa3b, v46
	v_exp_f32_e32 v92, v92
	v_fmamk_f32 v93, v46, 0x3c088889, v202
	v_fmaak_f32 v93, v46, v93, 0x3e2aaaab
	v_fma_f32 v93, v46, v93, 0.5
	v_fma_f32 v93, v46, v93, 1.0
	v_mul_f32_e64 v93, v93, -v46
	v_sub_f32_e32 v92, 1.0, v92
	v_cmp_nlt_f32_e32 vcc, s5, v46
	s_nop 1
	v_cndmask_b32_e32 v55, v93, v92, vcc
	v_and_b32_e32 v32, 0xffff0000, v32
	v_add_f32_e32 v32, v1, v32
	v_mul_f32_e32 v32, 0xbfb8aa3b, v32
	v_exp_f32_e32 v32, v32
	s_nop 0
	v_add_f32_e32 v32, 1.0, v32
	v_rcp_f32_e32 v32, v32
	s_nop 0
	v_mul_f32_e32 v66, v78, v32
	v_mul_f32_e32 v46, 0x3fb17218, v66
	v_mul_f32_e32 v92, 0x3fb8aa3b, v46
	v_exp_f32_e32 v92, v92
	v_fmamk_f32 v93, v46, 0x3c088889, v202
	v_fmaak_f32 v93, v46, v93, 0x3e2aaaab
	v_fma_f32 v93, v46, v93, 0.5
	v_fma_f32 v93, v46, v93, 1.0
	v_mul_f32_e64 v93, v93, -v46
	v_sub_f32_e32 v92, 1.0, v92
	v_cmp_nlt_f32_e32 vcc, s5, v46
	s_nop 1
	v_cndmask_b32_e32 v32, v93, v92, vcc
	v_lshlrev_b32_e32 v46, 16, v33
	v_add_f32_e32 v46, v2, v46
	v_mul_f32_e32 v46, 0xbfb8aa3b, v46
	v_exp_f32_e32 v46, v46
	s_nop 0
	v_add_f32_e32 v46, 1.0, v46
	v_rcp_f32_e32 v46, v46
	s_nop 0
	v_mul_f32_e32 v59, v77, v46
	v_mul_f32_e32 v46, 0x3fb17218, v59
	v_mul_f32_e32 v92, 0x3fb8aa3b, v46
	v_exp_f32_e32 v92, v92
	v_fmamk_f32 v93, v46, 0x3c088889, v202
	v_fmaak_f32 v93, v46, v93, 0x3e2aaaab
	v_fma_f32 v93, v46, v93, 0.5
	v_fma_f32 v93, v46, v93, 1.0
	v_mul_f32_e64 v93, v93, -v46
	v_sub_f32_e32 v92, 1.0, v92
	v_cmp_nlt_f32_e32 vcc, s5, v46
	s_nop 1
	v_cndmask_b32_e32 v57, v93, v92, vcc
	v_and_b32_e32 v33, 0xffff0000, v33
	v_add_f32_e32 v33, v3, v33
	v_mul_f32_e32 v33, 0xbfb8aa3b, v33
	v_exp_f32_e32 v33, v33
	s_nop 0
	v_add_f32_e32 v33, 1.0, v33
	v_rcp_f32_e32 v33, v33
	s_nop 0
	v_mul_f32_e32 v67, v76, v33
	v_mul_f32_e32 v46, 0x3fb17218, v67
	v_mul_f32_e32 v92, 0x3fb8aa3b, v46
	v_exp_f32_e32 v92, v92
	v_fmamk_f32 v93, v46, 0x3c088889, v202
	v_fmaak_f32 v93, v46, v93, 0x3e2aaaab
	v_fma_f32 v93, v46, v93, 0.5
	v_fma_f32 v93, v46, v93, 1.0
	v_mul_f32_e64 v93, v93, -v46
	v_sub_f32_e32 v92, 1.0, v92
	v_cmp_nlt_f32_e32 vcc, s5, v46
	s_nop 1
	v_cndmask_b32_e32 v33, v93, v92, vcc
	v_lshlrev_b32_e32 v46, 16, v34
	v_add_f32_e32 v46, v8, v46
	v_mul_f32_e32 v46, 0xbfb8aa3b, v46
	v_exp_f32_e32 v46, v46
	s_nop 0
	v_add_f32_e32 v46, 1.0, v46
	v_rcp_f32_e32 v46, v46
	s_nop 0
	v_mul_f32_e32 v49, v75, v46
	v_mul_f32_e32 v46, 0x3fb17218, v49
	v_mul_f32_e32 v92, 0x3fb8aa3b, v46
	v_exp_f32_e32 v92, v92
	v_fmamk_f32 v93, v46, 0x3c088889, v202
	v_fmaak_f32 v93, v46, v93, 0x3e2aaaab
	v_fma_f32 v93, v46, v93, 0.5
	v_fma_f32 v93, v46, v93, 1.0
	v_mul_f32_e64 v93, v93, -v46
	v_sub_f32_e32 v92, 1.0, v92
	v_cmp_nlt_f32_e32 vcc, s5, v46
	s_nop 1
	v_cndmask_b32_e32 v48, v93, v92, vcc
	v_and_b32_e32 v34, 0xffff0000, v34
	v_add_f32_e32 v34, v9, v34
	v_mul_f32_e32 v34, 0xbfb8aa3b, v34
	v_exp_f32_e32 v34, v34
	s_nop 0
	v_add_f32_e32 v34, 1.0, v34
	v_rcp_f32_e32 v34, v34
	s_nop 0
	v_mul_f32_e32 v51, v74, v34
	v_mul_f32_e32 v34, 0x3fb17218, v51
	v_mul_f32_e32 v92, 0x3fb8aa3b, v34
	v_exp_f32_e32 v92, v92
	v_fmamk_f32 v93, v34, 0x3c088889, v202
	v_fmaak_f32 v93, v34, v93, 0x3e2aaaab
	v_fma_f32 v93, v34, v93, 0.5
	v_fma_f32 v93, v34, v93, 1.0
	v_mul_f32_e64 v93, v93, -v34
	v_sub_f32_e32 v92, 1.0, v92
	v_cmp_nlt_f32_e32 vcc, s5, v34
	s_nop 1
	v_cndmask_b32_e32 v50, v93, v92, vcc
	v_lshlrev_b32_e32 v34, 16, v35
	v_add_f32_e32 v34, v10, v34
	v_mul_f32_e32 v34, 0xbfb8aa3b, v34
	v_exp_f32_e32 v34, v34
	s_nop 0
	v_add_f32_e32 v34, 1.0, v34
	v_rcp_f32_e32 v34, v34
	s_nop 0
	v_mul_f32_e32 v47, v73, v34
	v_mul_f32_e32 v34, 0x3fb17218, v47
	v_mul_f32_e32 v92, 0x3fb8aa3b, v34
	v_exp_f32_e32 v92, v92
	v_fmamk_f32 v93, v34, 0x3c088889, v202
	v_fmaak_f32 v93, v34, v93, 0x3e2aaaab
	v_fma_f32 v93, v34, v93, 0.5
	v_fma_f32 v93, v34, v93, 1.0
	v_mul_f32_e64 v93, v93, -v34
	v_sub_f32_e32 v92, 1.0, v92
	v_cmp_nlt_f32_e32 vcc, s5, v34
	s_nop 1
	v_cndmask_b32_e32 v46, v93, v92, vcc
	v_and_b32_e32 v34, 0xffff0000, v35
	v_add_f32_e32 v34, v11, v34
	v_mul_f32_e32 v34, 0xbfb8aa3b, v34
	v_exp_f32_e32 v34, v34
	s_nop 0
	v_add_f32_e32 v34, 1.0, v34
	v_rcp_f32_e32 v34, v34
	s_nop 0
	v_mul_f32_e32 v35, v80, v34
	v_mul_f32_e32 v61, 0x3fb17218, v35
	v_mul_f32_e32 v92, 0x3fb8aa3b, v61
	v_exp_f32_e32 v92, v92
	v_fmamk_f32 v93, v61, 0x3c088889, v202
	v_fmaak_f32 v93, v61, v93, 0x3e2aaaab
	v_fma_f32 v93, v61, v93, 0.5
	v_fma_f32 v93, v61, v93, 1.0
	v_mul_f32_e64 v93, v93, -v61
	v_sub_f32_e32 v92, 1.0, v92
	v_cmp_nlt_f32_e32 vcc, s5, v61
	s_nop 1
	v_cndmask_b32_e32 v34, v93, v92, vcc
	v_cmp_gt_f32_e32 vcc, s82, v47
	v_sqrt_f32_e32 v83, v46
	s_waitcnt vmcnt(0)
; __device__ __forceinline__ unsigned pk2(float lo, float hi) { f32x2_pk v = {lo, hi}; bf16x2_pk b = __builtin_convertvector(v, bf16x2_pk); return __builtin_bit_cast(unsigned, b); }
; __device__ __forceinline__ float sigmoidf_(float x) { return __builtin_amdgcn_rcpf(1.0f + __expf(-x)); }
; __device__ __forceinline__ void rg_unpack8(const u32x4 w, float* v) { v[0] = bflo(w.x); v[1] = bfhi(w.x); v[2] = bflo(w.y); v[3] = bfhi(w.y); v[4] = bflo(w.z); v[5] = bfhi(w.z); v[6] = bflo(w.w); v[7] = bfhi(w.w); }
; __device__ __forceinline__ void rg_ab(float ra, float ri, float x, float ba, float bx, float sp, float& a, float& b) {
;     const float r = sigmoidf_(ra + ba), ig = sigmoidf_(ri + bx); const float l2 = r * sp; a = exp2f(l2);
;     const float x2 = 1.3862943611198906f * l2;
;     const float om = x2 > -0.125f ? -x2 * (1.0f + x2 * (0.5f + x2 * (0.16666667f + x2 * (0.041666668f + x2 * 0.0083333338f)))) : 1.0f - __expf(x2);
;     b = __builtin_amdgcn_sqrtf(om) * (ig * x);
; }
; __device__ __forceinline__ void rg_scan2_phase(const bf16_t* RA0, bf16_t* RI0, const bf16_t* RA1, const bf16_t* RI1, const bf16_t* XCV, const float* bap, const float* bxp, const float* lamp, const float* CAR, bf16_t* Gb, int gtid, int ngt) {
;     ...
;         for (int i = 63; i >= 0; --i) { const size_t off = (size_t)(row0 + i) * DRNN + 8 * cg;
;             float ra[8], ri[8], xv[8], hf[8], gv[8]; rg_unpack8(*(const u32x4*)(RA1 + off), ra); rg_unpack8(*(const u32x4*)(RI1 + off), ri); rg_unpack8(*(const u32x4*)(XCV + off), xv);
;             rg_unpack8(*(const u32x4*)(RI0 + off), hf); rg_unpack8(*(const u32x4*)(Gb + off), gv);
; #pragma unroll
;             for (int e = 0; e < 8; ++e) { float a, bb; rg_ab(ra[e], ri[e], xv[e], ba[e], bx[e], sp[e], a, bb); h[e] = a * h[e] + bb; gv[e] *= hf[e] + h[e]; }
;             u32x4 o; o.x = pk2(gv[0], gv[1]); o.y = pk2(gv[2], gv[3]); o.z = pk2(gv[4], gv[5]); o.w = pk2(gv[6], gv[7]); *(u32x4*)(Gb + off) = o; }
	v_lshlrev_b32_e32 v65, 16, v31
	v_cndmask_b32_e32 v63, 0, v221, vcc
	v_add_f32_e32 v47, v47, v63
	v_lshlrev_b32_e32 v63, 16, v27
	v_add_f32_e32 v63, v14, v63
	v_mul_f32_e32 v63, 0xbfb8aa3b, v63
	v_exp_f32_e32 v47, v47
	v_exp_f32_e32 v63, v63
	v_cndmask_b32_e32 v61, 0, v220, vcc
	v_cmp_gt_f32_e32 vcc, s82, v35
	v_ldexp_f32 v82, v47, v61
	v_add_f32_e32 v61, 1.0, v63
	v_rcp_f32_e32 v61, v61
	v_lshlrev_b32_e32 v47, 16, v23
	v_lshlrev_b32_e32 v63, 16, v19
	s_mov_b64 s[2:3], 0x3026200
	v_mul_f32_e32 v71, v61, v47
	v_mul_f32_e32 v46, v71, v83
	v_pk_fma_f32 v[46:47], v[70:71], v[82:83], v[46:47] op_sel_hi:[1,1,0]
	v_cndmask_b32_e32 v61, 0, v220, vcc
	v_add_f32_e32 v47, v46, v63
	v_cndmask_b32_e32 v63, 0, v221, vcc
	v_cmp_gt_f32_e32 vcc, s82, v49
	v_mul_f32_e32 v47, v47, v65
	v_add_f32_e32 v35, v35, v63
	v_cndmask_b32_e32 v65, 0, v221, vcc
	v_add_f32_e32 v49, v49, v65
	v_lshlrev_b32_e32 v65, 16, v26
	v_add_f32_e32 v65, v12, v65
	v_mul_f32_e32 v65, 0xbfb8aa3b, v65
	v_exp_f32_e32 v49, v49
	v_exp_f32_e32 v65, v65
	v_cndmask_b32_e32 v63, 0, v220, vcc
	v_exp_f32_e32 v35, v35
	v_ldexp_f32 v82, v49, v63
	v_add_f32_e32 v49, 1.0, v65
	v_rcp_f32_e32 v49, v49
	v_and_b32_e32 v26, 0xffff0000, v26
	v_sqrt_f32_e32 v83, v48
	v_add_f32_e32 v26, v13, v26
	v_mul_f32_e32 v26, 0xbfb8aa3b, v26
	v_ldexp_f32 v70, v35, v61
	v_lshlrev_b32_e32 v35, 16, v22
	v_exp_f32_e32 v26, v26
	v_mul_f32_e32 v65, v49, v35
	v_mul_f32_e32 v48, v65, v83
	v_lshlrev_b32_e32 v61, 16, v18
	v_pk_fma_f32 v[48:49], v[64:65], v[82:83], v[48:49] op_sel_hi:[1,1,0]
	v_cmp_gt_f32_e32 vcc, s82, v51
	v_add_f32_e32 v35, v48, v61
	v_add_f32_e32 v26, 1.0, v26
	v_cndmask_b32_e32 v61, 0, v221, vcc
	v_add_f32_e32 v51, v51, v61
	v_rcp_f32_e32 v26, v26
	v_exp_f32_e32 v51, v51
	v_sqrt_f32_e32 v65, v50
	v_lshlrev_b32_e32 v63, 16, v30
	v_and_b32_e32 v22, 0xffff0000, v22
	v_cndmask_b32_e32 v49, 0, v220, vcc
	v_mul_f32_e32 v35, v35, v63
	v_mul_f32_e32 v63, v26, v22
	v_ldexp_f32 v64, v51, v49
	v_and_b32_e32 v49, 0xffff0000, v18
	v_mul_f32_e32 v18, v63, v65
	v_pk_fma_f32 v[50:51], v[62:63], v[64:65], v[18:19] op_sel_hi:[1,1,0]
	v_cmp_gt_f32_e32 vcc, s82, v59
	v_add_f32_e32 v18, v50, v49
	v_lshlrev_b32_e32 v49, 16, v25
	v_cndmask_b32_e32 v26, 0, v221, vcc
	v_add_f32_e32 v49, v6, v49
	v_add_f32_e32 v26, v59, v26
	v_mul_f32_e32 v49, 0xbfb8aa3b, v49
	v_exp_f32_e32 v26, v26
	v_exp_f32_e32 v49, v49
	v_cndmask_b32_e32 v22, 0, v220, vcc
	v_sqrt_f32_e32 v63, v57
	v_ldexp_f32 v62, v26, v22
	v_add_f32_e32 v22, 1.0, v49
	v_rcp_f32_e32 v22, v22
	v_and_b32_e32 v25, 0xffff0000, v25
	v_and_b32_e32 v30, 0xffff0000, v30
	v_add_f32_e32 v25, v7, v25
	v_mul_f32_e32 v30, v18, v30
	v_lshlrev_b32_e32 v18, 16, v21
	v_mul_f32_e32 v25, 0xbfb8aa3b, v25
	v_mul_f32_e32 v61, v22, v18
	v_exp_f32_e32 v25, v25
	v_mul_f32_e32 v18, v61, v63
	v_lshlrev_b32_e32 v26, 16, v17
	v_pk_fma_f32 v[60:61], v[60:61], v[62:63], v[18:19] op_sel_hi:[1,1,0]
	v_lshlrev_b32_e32 v49, 16, v29
	v_add_f32_e32 v18, v60, v26
	v_cmp_gt_f32_e32 vcc, s82, v67
	v_mul_f32_e32 v49, v18, v49
	v_and_b32_e32 v18, 0xffff0000, v21
	v_cndmask_b32_e32 v26, 0, v221, vcc
	v_add_f32_e32 v21, 1.0, v25
	v_add_f32_e32 v26, v67, v26
	v_rcp_f32_e32 v21, v21
	v_exp_f32_e32 v26, v26
	v_sqrt_f32_e32 v63, v33
	v_cndmask_b32_e32 v22, 0, v220, vcc
	v_mul_f32_e32 v59, v21, v18
	v_ldexp_f32 v62, v26, v22
	v_mul_f32_e32 v18, v59, v63
	v_pk_fma_f32 v[58:59], v[58:59], v[62:63], v[18:19] op_sel_hi:[1,1,0]
	v_lshlrev_b32_e32 v18, 16, v24
	v_add_f32_e32 v18, v4, v18
	v_mul_f32_e32 v18, 0xbfb8aa3b, v18
	v_exp_f32_e32 v18, v18
	v_cmp_gt_f32_e32 vcc, s82, v53
	v_sqrt_f32_e32 v63, v55
	v_lshlrev_b32_e32 v21, 16, v20
	v_cndmask_b32_e32 v26, 0, v221, vcc
	v_add_f32_e32 v18, 1.0, v18
	v_add_f32_e32 v26, v53, v26
	v_rcp_f32_e32 v18, v18
	v_exp_f32_e32 v26, v26
	v_and_b32_e32 v17, 0xffff0000, v17
	v_cndmask_b32_e32 v25, 0, v220, vcc
	v_mul_f32_e32 v57, v18, v21
	v_and_b32_e32 v22, 0xffff0000, v29
	v_add_f32_e32 v17, v58, v17
	v_ldexp_f32 v62, v26, v25
	v_mul_f32_e32 v18, v57, v63
	v_mul_f32_e32 v17, v17, v22
	v_lshlrev_b32_e32 v22, 16, v16
	v_pk_fma_f32 v[56:57], v[56:57], v[62:63], v[18:19] op_sel_hi:[1,1,0]
	v_cmp_gt_f32_e32 vcc, s82, v66
	v_and_b32_e32 v24, 0xffff0000, v24
	v_add_f32_e32 v18, v56, v22
	v_cndmask_b32_e32 v22, 0, v221, vcc
	v_add_f32_e32 v24, v5, v24
	v_add_f32_e32 v22, v66, v22
	v_mul_f32_e32 v24, 0xbfb8aa3b, v24
	v_exp_f32_e32 v22, v22
	v_exp_f32_e32 v25, v24
	v_cndmask_b32_e32 v21, 0, v220, vcc
	v_and_b32_e32 v20, 0xffff0000, v20
	v_ldexp_f32 v24, v22, v21
	v_add_f32_e32 v21, 1.0, v25
	v_rcp_f32_e32 v21, v21
	v_sqrt_f32_e32 v25, v32
	v_and_b32_e32 v22, 0xffff0000, v16
	v_sqrt_f32_e32 v71, v34
	v_mul_f32_e32 v55, v21, v20
	v_mul_f32_e32 v16, v55, v25
	v_pk_fma_f32 v[54:55], v[54:55], v[24:25], v[16:17] op_sel_hi:[1,1,0]
	v_and_b32_e32 v16, 0xffff0000, v27
	v_add_f32_e32 v16, v15, v16
	v_mul_f32_e32 v16, 0xbfb8aa3b, v16
	v_exp_f32_e32 v16, v16
	v_and_b32_e32 v21, 0xffff0000, v23
	v_and_b32_e32 v19, 0xffff0000, v19
	v_lshlrev_b32_e32 v29, 16, v28
	v_add_f32_e32 v16, 1.0, v16
	v_rcp_f32_e32 v16, v16
	v_and_b32_e32 v26, 0xffff0000, v28
	v_add_f32_e32 v20, v54, v22
	v_and_b32_e32 v22, 0xffff0000, v31
	v_mul_f32_e32 v53, v16, v21
	v_mul_f32_e32 v16, v53, v71
	v_pk_fma_f32 v[62:63], v[52:53], v[70:71], v[16:17] op_sel_hi:[1,1,0]
	v_mul_f32_e32 v18, v18, v29
	v_add_f32_e32 v16, v62, v19
	v_mul_f32_e32 v20, v20, v26
	v_mul_f32_e32 v19, v16, v22
	v_lshl_add_u64 v[68:69], v[42:43], 0, s[2:3]
	v_cvt_pk_bf16_f32 v16, v18, v20
	v_cvt_pk_bf16_f32 v17, v49, v17
	v_cvt_pk_bf16_f32 v18, v35, v30
	v_cvt_pk_bf16_f32 v19, v47, v19
	s_mov_b32 s2, 0x19825000
	global_store_dwordx4 v[68:69], v[16:19], off
	s_nop 1
; __device__ __forceinline__ unsigned pk2(float lo, float hi) { f32x2_pk v = {lo, hi}; bf16x2_pk b = __builtin_convertvector(v, bf16x2_pk); return __builtin_bit_cast(unsigned, b); }
; __device__ __forceinline__ float sigmoidf_(float x) { return __builtin_amdgcn_rcpf(1.0f + __expf(-x)); }
; __device__ __forceinline__ void rg_unpack8(const u32x4 w, float* v) { v[0] = bflo(w.x); v[1] = bfhi(w.x); v[2] = bflo(w.y); v[3] = bfhi(w.y); v[4] = bflo(w.z); v[5] = bfhi(w.z); v[6] = bflo(w.w); v[7] = bfhi(w.w); }
; __device__ __forceinline__ void rg_ab(float ra, float ri, float x, float ba, float bx, float sp, float& a, float& b) {
;     const float r = sigmoidf_(ra + ba), ig = sigmoidf_(ri + bx); const float l2 = r * sp; a = exp2f(l2);
;     const float x2 = 1.3862943611198906f * l2;
;     const float om = x2 > -0.125f ? -x2 * (1.0f + x2 * (0.5f + x2 * (0.16666667f + x2 * (0.041666668f + x2 * 0.0083333338f)))) : 1.0f - __expf(x2);
;     b = __builtin_amdgcn_sqrtf(om) * (ig * x);
; }
; __device__ __forceinline__ void rg_scan2_phase(const bf16_t* RA0, bf16_t* RI0, const bf16_t* RA1, const bf16_t* RI1, const bf16_t* XCV, const float* bap, const float* bxp, const float* lamp, const float* CAR, bf16_t* Gb, int gtid, int ngt) {
;     ...
;         for (int i = 63; i >= 0; --i) { const size_t off = (size_t)(row0 + i) * DRNN + 8 * cg;
;             float ra[8], ri[8], xv[8], hf[8], gv[8]; rg_unpack8(*(const u32x4*)(RA1 + off), ra); rg_unpack8(*(const u32x4*)(RI1 + off), ri); rg_unpack8(*(const u32x4*)(XCV + off), xv);
;             rg_unpack8(*(const u32x4*)(RI0 + off), hf); rg_unpack8(*(const u32x4*)(Gb + off), gv);
; #pragma unroll
;             for (int e = 0; e < 8; ++e) { float a, bb; rg_ab(ra[e], ri[e], xv[e], ba[e], bx[e], sp[e], a, bb); h[e] = a * h[e] + bb; gv[e] *= hf[e] + h[e]; }
;             u32x4 o; o.x = pk2(gv[0], gv[1]); o.y = pk2(gv[2], gv[3]); o.z = pk2(gv[4], gv[5]); o.w = pk2(gv[6], gv[7]); *(u32x4*)(Gb + off) = o; }
	v_add_co_u32_e32 v16, vcc, s2, v42
	s_mov_b32 s2, 0x25000
	s_nop 0
	v_addc_co_u32_e32 v17, vcc, 0, v43, vcc
	s_nop 1
	v_mov_b32_e32 v32, v168
	v_mov_b32_e32 v33, v169
	v_mov_b32_e32 v34, v170
	v_mov_b32_e32 v35, v171
	global_load_dwordx4 v[168:171], v[16:17], off offset:-512
	v_add_co_u32_e32 v16, vcc, s2, v44
	s_mov_b32 s2, 0x8a25000
	s_nop 0
	v_addc_co_u32_e32 v17, vcc, 0, v45, vcc
	v_add_co_u32_e32 v20, vcc, s2, v42
	s_mov_b32 s2, 0x13e25000
	s_nop 0
	v_addc_co_u32_e32 v21, vcc, 0, v43, vcc
	v_add_co_u32_e32 v22, vcc, s2, v42
	global_load_dwordx4 v[16:19], v[16:17], off offset:2048
	s_nop 0
	v_addc_co_u32_e32 v23, vcc, 0, v43, vcc
	v_add_co_u32_e32 v28, vcc, 0x3025000, v42
	global_load_dwordx4 v[24:27], v[20:21], off offset:2048
	s_nop 0
	global_load_dwordx4 v[20:23], v[22:23], off offset:2048
	v_addc_co_u32_e32 v29, vcc, 0, v43, vcc
	global_load_dwordx4 v[28:31], v[28:29], off offset:2048
	s_nop 0
	v_lshlrev_b32_e32 v44, 16, v32
	v_add_f32_e32 v44, v0, v44
	v_mul_f32_e32 v44, 0xbfb8aa3b, v44
	v_exp_f32_e32 v44, v44
	s_nop 0
	v_add_f32_e32 v44, 1.0, v44
	v_rcp_f32_e32 v44, v44
	s_nop 0
	v_mul_f32_e32 v44, v79, v44
	v_mul_f32_e32 v47, 0x3fb17218, v44
	v_mul_f32_e32 v92, 0x3fb8aa3b, v47
	v_exp_f32_e32 v92, v92
	v_fmamk_f32 v93, v47, 0x3c088889, v202
	v_fmaak_f32 v93, v47, v93, 0x3e2aaaab
	v_fma_f32 v93, v47, v93, 0.5
	v_fma_f32 v93, v47, v93, 1.0
	v_mul_f32_e64 v93, v93, -v47
	v_sub_f32_e32 v92, 1.0, v92
	v_cmp_nlt_f32_e32 vcc, s5, v47
	s_nop 1
	v_cndmask_b32_e32 v45, v93, v92, vcc
	v_and_b32_e32 v32, 0xffff0000, v32
	v_add_f32_e32 v32, v1, v32
	v_mul_f32_e32 v32, 0xbfb8aa3b, v32
	v_exp_f32_e32 v32, v32
	s_nop 0
	v_add_f32_e32 v32, 1.0, v32
	v_rcp_f32_e32 v32, v32
	s_nop 0
	v_mul_f32_e32 v32, v78, v32
	v_mul_f32_e32 v49, 0x3fb17218, v32
	v_mul_f32_e32 v92, 0x3fb8aa3b, v49
	v_exp_f32_e32 v92, v92
	v_fmamk_f32 v93, v49, 0x3c088889, v202
	v_fmaak_f32 v93, v49, v93, 0x3e2aaaab
	v_fma_f32 v93, v49, v93, 0.5
	v_fma_f32 v93, v49, v93, 1.0
	v_mul_f32_e64 v93, v93, -v49
	v_sub_f32_e32 v92, 1.0, v92
	v_cmp_nlt_f32_e32 vcc, s5, v49
	s_nop 1
	v_cndmask_b32_e32 v47, v93, v92, vcc
	v_lshlrev_b32_e32 v49, 16, v33
	v_add_f32_e32 v49, v2, v49
	v_mul_f32_e32 v49, 0xbfb8aa3b, v49
	v_exp_f32_e32 v49, v49
	s_nop 0
	v_add_f32_e32 v49, 1.0, v49
	v_rcp_f32_e32 v49, v49
	s_nop 0
	v_mul_f32_e32 v49, v77, v49
	v_mul_f32_e32 v52, 0x3fb17218, v49
	v_mul_f32_e32 v92, 0x3fb8aa3b, v52
	v_exp_f32_e32 v92, v92
	v_fmamk_f32 v93, v52, 0x3c088889, v202
	v_fmaak_f32 v93, v52, v93, 0x3e2aaaab
	v_fma_f32 v93, v52, v93, 0.5
	v_fma_f32 v93, v52, v93, 1.0
	v_mul_f32_e64 v93, v93, -v52
	v_sub_f32_e32 v92, 1.0, v92
	v_cmp_nlt_f32_e32 vcc, s5, v52
	s_nop 1
	v_cndmask_b32_e32 v51, v93, v92, vcc
	v_and_b32_e32 v33, 0xffff0000, v33
	v_add_f32_e32 v33, v3, v33
	v_mul_f32_e32 v33, 0xbfb8aa3b, v33
	v_exp_f32_e32 v33, v33
	s_nop 0
	v_add_f32_e32 v33, 1.0, v33
	v_rcp_f32_e32 v33, v33
	s_nop 0
	v_mul_f32_e32 v33, v76, v33
	v_mul_f32_e32 v53, 0x3fb17218, v33
	v_mul_f32_e32 v92, 0x3fb8aa3b, v53
	v_exp_f32_e32 v92, v92
	v_fmamk_f32 v93, v53, 0x3c088889, v202
	v_fmaak_f32 v93, v53, v93, 0x3e2aaaab
	v_fma_f32 v93, v53, v93, 0.5
	v_fma_f32 v93, v53, v93, 1.0
	v_mul_f32_e64 v93, v93, -v53
	v_sub_f32_e32 v92, 1.0, v92
	v_cmp_nlt_f32_e32 vcc, s5, v53
	s_nop 1
	v_cndmask_b32_e32 v52, v93, v92, vcc
	v_lshlrev_b32_e32 v53, 16, v34
	v_add_f32_e32 v53, v8, v53
	v_mul_f32_e32 v53, 0xbfb8aa3b, v53
	v_exp_f32_e32 v53, v53
	s_nop 0
	v_add_f32_e32 v53, 1.0, v53
	v_rcp_f32_e32 v53, v53
	s_nop 0
	v_mul_f32_e32 v53, v75, v53
	v_mul_f32_e32 v55, 0x3fb17218, v53
	v_mul_f32_e32 v92, 0x3fb8aa3b, v55
	v_exp_f32_e32 v92, v92
	v_fmamk_f32 v93, v55, 0x3c088889, v202
	v_fmaak_f32 v93, v55, v93, 0x3e2aaaab
	v_fma_f32 v93, v55, v93, 0.5
	v_fma_f32 v93, v55, v93, 1.0
	v_mul_f32_e64 v93, v93, -v55
	v_sub_f32_e32 v92, 1.0, v92
	v_cmp_nlt_f32_e32 vcc, s5, v55
	s_nop 1
	v_cndmask_b32_e32 v63, v93, v92, vcc
	v_and_b32_e32 v34, 0xffff0000, v34
	v_add_f32_e32 v34, v9, v34
	v_mul_f32_e32 v34, 0xbfb8aa3b, v34
	v_exp_f32_e32 v34, v34
	s_nop 0
	v_add_f32_e32 v34, 1.0, v34
	v_rcp_f32_e32 v34, v34
	s_nop 0
	v_mul_f32_e32 v34, v74, v34
	v_mul_f32_e32 v55, 0x3fb17218, v34
	v_mul_f32_e32 v92, 0x3fb8aa3b, v55
	v_exp_f32_e32 v92, v92
	v_fmamk_f32 v93, v55, 0x3c088889, v202
	v_fmaak_f32 v93, v55, v93, 0x3e2aaaab
	v_fma_f32 v93, v55, v93, 0.5
	v_fma_f32 v93, v55, v93, 1.0
	v_mul_f32_e64 v93, v93, -v55
	v_sub_f32_e32 v92, 1.0, v92
	v_cmp_nlt_f32_e32 vcc, s5, v55
	s_nop 1
	v_cndmask_b32_e32 v64, v93, v92, vcc
	v_lshlrev_b32_e32 v55, 16, v35
	v_add_f32_e32 v55, v10, v55
	v_mul_f32_e32 v55, 0xbfb8aa3b, v55
	v_exp_f32_e32 v55, v55
	s_nop 0
	v_add_f32_e32 v55, 1.0, v55
	v_rcp_f32_e32 v55, v55
	s_nop 0
	v_mul_f32_e32 v66, v73, v55
	v_mul_f32_e32 v55, 0x3fb17218, v66
	v_mul_f32_e32 v92, 0x3fb8aa3b, v55
	v_exp_f32_e32 v92, v92
	v_fmamk_f32 v93, v55, 0x3c088889, v202
	v_fmaak_f32 v93, v55, v93, 0x3e2aaaab
	v_fma_f32 v93, v55, v93, 0.5
	v_fma_f32 v93, v55, v93, 1.0
	v_mul_f32_e64 v93, v93, -v55
	v_sub_f32_e32 v92, 1.0, v92
	v_cmp_nlt_f32_e32 vcc, s5, v55
	s_nop 1
	v_cndmask_b32_e32 v65, v93, v92, vcc
	v_and_b32_e32 v35, 0xffff0000, v35
	v_add_f32_e32 v35, v11, v35
	v_mul_f32_e32 v35, 0xbfb8aa3b, v35
	v_exp_f32_e32 v35, v35
	s_nop 0
	v_add_f32_e32 v35, 1.0, v35
	v_rcp_f32_e32 v35, v35
	s_nop 0
	v_mul_f32_e32 v67, v80, v35
	v_mul_f32_e32 v55, 0x3fb17218, v67
	v_cmp_nlt_f32_e32 vcc, s5, v55
	s_and_saveexec_b64 s[2:3], vcc
	s_xor_b64 s[6:7], exec, s[2:3]
	v_mul_f32_e32 v35, 0x3fb8aa3b, v55
	v_exp_f32_e32 v35, v35
	s_nop 0
	v_sub_f32_e32 v35, 1.0, v35
	s_andn2_saveexec_b64 s[6:7], s[6:7]
	s_cbranch_execz .LBB0_1416
	v_fmamk_f32 v35, v55, 0x3c088889, v202
	v_fmaak_f32 v35, v55, v35, 0x3e2aaaab
	v_fma_f32 v35, v55, v35, 0.5
	v_fma_f32 v35, v55, v35, 1.0
	v_mul_f32_e64 v35, v35, -v55
	s_branch .LBB0_1416
